# up-GEMM conv epilogue second half: all 16 conv-weight LDS reads hoisted to the half's start into free registers (groups then wait only on the 2 boundary-row reads)
# baseline (speedup 1.0000x reference)
;     __device__ __forceinline__ void run(f32x4 (&acc)[2][2][4][2], const Unit& u, int wr, int wc, int fr_, int fq_, int par) const {
;     ...
;         for (int ai = 0; ai < 2; ++ai)
; #pragma unroll
;             for (int m = 0; m < 4; ++m) { const float sc = rsl[ai * HALF + wr * 64 + 4 * fr + m];
; #pragma unroll
;                 for (int bj = 0; bj < 2; ++bj)
; #pragma unroll
;                     for (int n = 0; n < 2; ++n) acc[ai][bj][m][n] = acc[ai][bj][m][n] * sc; }
;     ...
;         for (int ai = 0; ai < 2; ++ai) {
;             const bool has_prev = (wr | ai) != 0;
;             const int swr = wr ^ 1, sai = wr ? ai : 0;
;             const int growu = a_row0 + u.pm * a_rstep + ai * HALF + wr * 64;
;             const int grow0 = growu + 4 * fr;
;             const int tz = ((grow0 % seqlen) + seqlen) % seqlen;
.LBB0_605:
	s_or_b64 exec, exec, s[4:5]
	ds_read_b128 v[154:157], v249
	ds_read_b128 v[158:161], v249 offset:1024
	ds_read_b128 v[162:165], v249 offset:2048
	ds_read_b128 v[168:171], v249 offset:3072
	ds_read_b128 v[172:175], v249 offset:16
	ds_read_b128 v[176:179], v249 offset:1040
	ds_read_b128 v[180:183], v249 offset:2064
	ds_read_b128 v[184:187], v249 offset:3088
	ds_read_b128 v[188:191], v249 offset:512
	ds_read_b128 v[192:195], v249 offset:1536
	ds_read_b128 v[196:199], v249 offset:2560
	ds_read_b128 v[208:211], v249 offset:3584
	ds_read_b128 v[212:215], v249 offset:528
	ds_read_b128 v[216:219], v249 offset:1552
	ds_read_b128 v[220:223], v249 offset:2576
	ds_read_b128 v[224:227], v249 offset:3600
	v_pk_mul_f32 v[122:123], v[34:35], v[66:67] op_sel_hi:[1,0]
	v_pk_mul_f32 v[124:125], v[36:37], v[66:67] op_sel_hi:[1,0]
	v_pk_mul_f32 v[114:115], v[30:31], v[66:67] op_sel_hi:[1,0]
	v_pk_mul_f32 v[116:117], v[32:33], v[66:67] op_sel_hi:[1,0]
	v_pk_mul_f32 v[106:107], v[14:15], v[66:67] op_sel_hi:[1,0]
	v_pk_mul_f32 v[108:109], v[16:17], v[66:67] op_sel_hi:[1,0]
	v_pk_mul_f32 v[98:99], v[10:11], v[66:67] op_sel_hi:[1,0]
	v_pk_mul_f32 v[100:101], v[12:13], v[66:67] op_sel_hi:[1,0]
	v_pk_mul_f32 v[126:127], v[22:23], v[66:67] op_sel:[0,1]
	v_pk_mul_f32 v[128:129], v[24:25], v[66:67] op_sel:[0,1]
	v_pk_mul_f32 v[118:119], v[18:19], v[66:67] op_sel:[0,1]
	v_pk_mul_f32 v[120:121], v[20:21], v[66:67] op_sel:[0,1]
	v_pk_mul_f32 v[110:111], v[6:7], v[66:67] op_sel:[0,1]
	v_pk_mul_f32 v[112:113], v[8:9], v[66:67] op_sel:[0,1]
	v_pk_mul_f32 v[102:103], v[2:3], v[66:67] op_sel:[0,1]
	v_pk_mul_f32 v[104:105], v[4:5], v[66:67] op_sel:[0,1]
	s_add_i32 s14, s43, s14
	v_add_u32_e32 v132, s14, v251
	v_mul_hi_i32 v2, v132, s62
	v_lshrrev_b32_e32 v3, 31, v2
	v_ashrrev_i32_e32 v2, 7, v2
	v_add_u32_e32 v2, v2, v3
	s_movk_i32 s4, 0x810
	v_mul_lo_u32 v2, v2, s4
	v_sub_u32_e32 v2, v132, v2
	v_add_u32_e32 v3, 0x810, v2
	v_cmp_gt_i32_e32 vcc, 0, v2
	s_movk_i32 s4, 0xf7f5
	v_lshl_add_u32 v133, v250, 4, v247
	v_cndmask_b32_e32 v2, v2, v3, vcc
	v_add_u32_e32 v3, 0xfffff7f3, v2
	v_cmp_gt_u32_e32 vcc, s4, v3
	s_cbranch_vccz .LBB0_623
	ds_read_b128 v[4:7], v133
	ds_read_b128 v[8:11], v133 offset:256
	s_waitcnt lgkmcnt(0)
	v_mov_b32_dpp v6, v60 row_shr:1 row_mask:0xf bank_mask:0xf
	v_mov_b32_dpp v7, v61 row_shr:1 row_mask:0xf bank_mask:0xf
	v_cmp_eq_u32_e32 vcc, 0, v2
	v_mov_b32_dpp v4, v58 row_shr:1 row_mask:0xf bank_mask:0xf
	v_mov_b32_dpp v5, v59 row_shr:1 row_mask:0xf bank_mask:0xf
	v_mov_b32_dpp v10, v64 row_shr:1 row_mask:0xf bank_mask:0xf
	v_mov_b32_dpp v11, v65 row_shr:1 row_mask:0xf bank_mask:0xf
	v_cndmask_b32_e64 v7, v7, 0, vcc
	v_cndmask_b32_e64 v6, v6, 0, vcc
	v_mov_b32_dpp v8, v62 row_shr:1 row_mask:0xf bank_mask:0xf
	v_mov_b32_dpp v9, v63 row_shr:1 row_mask:0xf bank_mask:0xf
	v_cndmask_b32_e64 v11, v11, 0, vcc
	v_cndmask_b32_e64 v10, v10, 0, vcc
	v_cndmask_b32_e64 v5, v5, 0, vcc
	v_cndmask_b32_e64 v4, v4, 0, vcc
	v_pk_fma_f32 v[6:7], v[156:157], v[6:7], v[170:171]
	v_cndmask_b32_e64 v9, v9, 0, vcc
	v_cndmask_b32_e64 v8, v8, 0, vcc
	v_pk_fma_f32 v[4:5], v[154:155], v[4:5], v[168:169]
	v_pk_fma_f32 v[6:7], v[160:161], v[10:11], v[6:7]
	v_pk_fma_f32 v[4:5], v[158:159], v[8:9], v[4:5]
	v_pk_fma_f32 v[68:69], v[124:125], v[164:165], v[6:7]
	v_pk_fma_f32 v[6:7], v[154:155], v[8:9], v[168:169]
	s_movk_i32 s4, 0x80e
	v_pk_fma_f32 v[66:67], v[122:123], v[162:163], v[4:5]
	v_pk_fma_f32 v[4:5], v[156:157], v[10:11], v[170:171]
	v_pk_fma_f32 v[6:7], v[122:123], v[158:159], v[6:7]
	v_cmp_eq_u32_e64 s[4:5], s4, v2
	v_pk_fma_f32 v[4:5], v[124:125], v[160:161], v[4:5]
	v_pk_fma_f32 v[18:19], v[126:127], v[162:163], v[6:7]
	v_cndmask_b32_e64 v7, v123, 0, s[4:5]
	v_cndmask_b32_e64 v6, v122, 0, s[4:5]
	v_cndmask_b32_e64 v9, v125, 0, s[4:5]
	v_cndmask_b32_e64 v8, v124, 0, s[4:5]
	v_pk_fma_f32 v[20:21], v[128:129], v[164:165], v[4:5]
	v_cndmask_b32_e64 v3, v129, 0, s[4:5]
	v_cndmask_b32_e64 v2, v128, 0, s[4:5]
	v_cndmask_b32_e64 v5, v127, 0, s[4:5]
	v_cndmask_b32_e64 v4, v126, 0, s[4:5]
	v_pk_fma_f32 v[8:9], v[8:9], v[156:157], v[170:171]
	v_pk_fma_f32 v[6:7], v[6:7], v[154:155], v[168:169]
	v_pk_fma_f32 v[8:9], v[2:3], v[160:161], v[8:9]
	v_pk_fma_f32 v[6:7], v[4:5], v[158:159], v[6:7]
	v_pk_fma_f32 v[2:3], v[2:3], v[156:157], v[170:171]
	v_pk_fma_f32 v[4:5], v[4:5], v[154:155], v[168:169]
	v_pk_fma_f32 v[10:11], v[58:59], v[162:163], v[6:7]
	v_pk_fma_f32 v[6:7], v[58:59], v[158:159], v[4:5]
	v_pk_fma_f32 v[2:3], v[60:61], v[160:161], v[2:3]
	v_pk_fma_f32 v[12:13], v[60:61], v[164:165], v[8:9]
	v_pk_fma_f32 v[4:5], v[64:65], v[164:165], v[2:3]
	v_pk_fma_f32 v[2:3], v[62:63], v[162:163], v[6:7]
	ds_read_b128 v[6:9], v133 offset:64
	ds_read_b128 v[14:17], v133 offset:320
	s_waitcnt lgkmcnt(0)
	v_mov_b32_dpp v6, v50 row_shr:1 row_mask:0xf bank_mask:0xf
	v_mov_b32_dpp v7, v51 row_shr:1 row_mask:0xf bank_mask:0xf
	v_mov_b32_dpp v8, v52 row_shr:1 row_mask:0xf bank_mask:0xf
	v_mov_b32_dpp v9, v53 row_shr:1 row_mask:0xf bank_mask:0xf
	v_mov_b32_dpp v14, v54 row_shr:1 row_mask:0xf bank_mask:0xf
	v_mov_b32_dpp v15, v55 row_shr:1 row_mask:0xf bank_mask:0xf
	v_mov_b32_dpp v16, v56 row_shr:1 row_mask:0xf bank_mask:0xf
	v_mov_b32_dpp v17, v57 row_shr:1 row_mask:0xf bank_mask:0xf
	v_cndmask_b32_e64 v7, v7, 0, vcc
	v_cndmask_b32_e64 v6, v6, 0, vcc
	v_cndmask_b32_e64 v9, v9, 0, vcc
	v_cndmask_b32_e64 v8, v8, 0, vcc
	v_cndmask_b32_e64 v17, v17, 0, vcc
	v_cndmask_b32_e64 v16, v16, 0, vcc
	v_cndmask_b32_e64 v15, v15, 0, vcc
	v_cndmask_b32_e64 v14, v14, 0, vcc
	v_pk_fma_f32 v[8:9], v[174:175], v[8:9], v[186:187]
	v_pk_fma_f32 v[6:7], v[172:173], v[6:7], v[184:185]
	v_pk_fma_f32 v[8:9], v[178:179], v[16:17], v[8:9]
	v_pk_fma_f32 v[6:7], v[176:177], v[14:15], v[6:7]
	v_pk_fma_f32 v[76:77], v[116:117], v[182:183], v[8:9]
	v_pk_fma_f32 v[74:75], v[114:115], v[180:181], v[6:7]
	v_pk_fma_f32 v[6:7], v[174:175], v[16:17], v[186:187]
	v_pk_fma_f32 v[8:9], v[172:173], v[14:15], v[184:185]
	v_pk_fma_f32 v[6:7], v[116:117], v[178:179], v[6:7]
	v_pk_fma_f32 v[8:9], v[114:115], v[176:177], v[8:9]
	v_cndmask_b32_e64 v15, v117, 0, s[4:5]
	v_cndmask_b32_e64 v14, v116, 0, s[4:5]
	v_cndmask_b32_e64 v17, v115, 0, s[4:5]
	v_cndmask_b32_e64 v16, v114, 0, s[4:5]
	v_pk_fma_f32 v[32:33], v[120:121], v[182:183], v[6:7]
	v_pk_fma_f32 v[30:31], v[118:119], v[180:181], v[8:9]
	v_cndmask_b32_e64 v7, v119, 0, s[4:5]
	v_cndmask_b32_e64 v6, v118, 0, s[4:5]
	v_cndmask_b32_e64 v9, v121, 0, s[4:5]
	v_cndmask_b32_e64 v8, v120, 0, s[4:5]
	v_pk_fma_f32 v[16:17], v[16:17], v[172:173], v[184:185]
	v_pk_fma_f32 v[14:15], v[14:15], v[174:175], v[186:187]
	s_nop 0
	v_pk_fma_f32 v[82:83], v[8:9], v[178:179], v[14:15]
	v_pk_fma_f32 v[14:15], v[6:7], v[176:177], v[16:17]
	v_pk_fma_f32 v[6:7], v[6:7], v[172:173], v[184:185]
	v_pk_fma_f32 v[8:9], v[8:9], v[174:175], v[186:187]
	v_pk_fma_f32 v[6:7], v[50:51], v[176:177], v[6:7]
	v_pk_fma_f32 v[8:9], v[52:53], v[178:179], v[8:9]
	v_pk_fma_f32 v[14:15], v[50:51], v[180:181], v[14:15]
	v_pk_fma_f32 v[16:17], v[52:53], v[182:183], v[82:83]
	v_pk_fma_f32 v[6:7], v[54:55], v[180:181], v[6:7]
	v_pk_fma_f32 v[8:9], v[56:57], v[182:183], v[8:9]
	ds_read_b128 v[22:25], v133 offset:128
	ds_read_b128 v[34:37], v133 offset:384
	s_waitcnt lgkmcnt(0)
	v_mov_b32_dpp v22, v42 row_shr:1 row_mask:0xf bank_mask:0xf
	v_mov_b32_dpp v23, v43 row_shr:1 row_mask:0xf bank_mask:0xf
	v_mov_b32_dpp v24, v44 row_shr:1 row_mask:0xf bank_mask:0xf
	v_mov_b32_dpp v25, v45 row_shr:1 row_mask:0xf bank_mask:0xf
	v_mov_b32_dpp v34, v46 row_shr:1 row_mask:0xf bank_mask:0xf
	v_mov_b32_dpp v35, v47 row_shr:1 row_mask:0xf bank_mask:0xf
	v_mov_b32_dpp v36, v48 row_shr:1 row_mask:0xf bank_mask:0xf
	v_mov_b32_dpp v37, v49 row_shr:1 row_mask:0xf bank_mask:0xf
	v_cndmask_b32_e64 v23, v23, 0, vcc
	v_cndmask_b32_e64 v22, v22, 0, vcc
	v_cndmask_b32_e64 v25, v25, 0, vcc
	v_cndmask_b32_e64 v24, v24, 0, vcc
	v_cndmask_b32_e64 v37, v37, 0, vcc
	v_cndmask_b32_e64 v36, v36, 0, vcc
	v_cndmask_b32_e64 v35, v35, 0, vcc
	v_cndmask_b32_e64 v34, v34, 0, vcc
	v_pk_fma_f32 v[24:25], v[190:191], v[24:25], v[210:211]
	v_pk_fma_f32 v[22:23], v[188:189], v[22:23], v[208:209]
	v_pk_fma_f32 v[24:25], v[194:195], v[36:37], v[24:25]
	v_pk_fma_f32 v[22:23], v[192:193], v[34:35], v[22:23]
	v_pk_fma_f32 v[92:93], v[108:109], v[198:199], v[24:25]
	v_pk_fma_f32 v[90:91], v[106:107], v[196:197], v[22:23]
	v_pk_fma_f32 v[22:23], v[190:191], v[36:37], v[210:211]
	v_pk_fma_f32 v[24:25], v[188:189], v[34:35], v[208:209]
	v_pk_fma_f32 v[22:23], v[108:109], v[194:195], v[22:23]
	v_pk_fma_f32 v[24:25], v[106:107], v[192:193], v[24:25]
	v_cndmask_b32_e64 v35, v109, 0, s[4:5]
	v_cndmask_b32_e64 v34, v108, 0, s[4:5]
	v_cndmask_b32_e64 v37, v107, 0, s[4:5]
	v_cndmask_b32_e64 v36, v106, 0, s[4:5]
	v_pk_fma_f32 v[84:85], v[112:113], v[198:199], v[22:23]
	v_pk_fma_f32 v[82:83], v[110:111], v[196:197], v[24:25]
	v_cndmask_b32_e64 v23, v111, 0, s[4:5]
	v_cndmask_b32_e64 v22, v110, 0, s[4:5]
	v_cndmask_b32_e64 v25, v113, 0, s[4:5]
	v_cndmask_b32_e64 v24, v112, 0, s[4:5]
	v_pk_fma_f32 v[36:37], v[36:37], v[188:189], v[208:209]
	v_pk_fma_f32 v[34:35], v[34:35], v[190:191], v[210:211]
	v_pk_fma_f32 v[36:37], v[22:23], v[192:193], v[36:37]
	v_pk_fma_f32 v[34:35], v[24:25], v[194:195], v[34:35]
	v_pk_fma_f32 v[22:23], v[22:23], v[188:189], v[208:209]
	v_pk_fma_f32 v[24:25], v[24:25], v[190:191], v[210:211]
	v_pk_fma_f32 v[22:23], v[42:43], v[192:193], v[22:23]
	v_pk_fma_f32 v[24:25], v[44:45], v[194:195], v[24:25]
	v_pk_fma_f32 v[70:71], v[42:43], v[196:197], v[36:37]
	v_pk_fma_f32 v[72:73], v[44:45], v[198:199], v[34:35]
	v_pk_fma_f32 v[22:23], v[46:47], v[196:197], v[22:23]
	v_pk_fma_f32 v[24:25], v[48:49], v[198:199], v[24:25]
	ds_read_b128 v[34:37], v133 offset:192
	ds_read_b128 v[78:81], v133 offset:448
	s_waitcnt lgkmcnt(0)
	v_mov_b32_dpp v34, v26 row_shr:1 row_mask:0xf bank_mask:0xf
	v_mov_b32_dpp v35, v27 row_shr:1 row_mask:0xf bank_mask:0xf
	v_mov_b32_dpp v36, v28 row_shr:1 row_mask:0xf bank_mask:0xf
	v_mov_b32_dpp v37, v29 row_shr:1 row_mask:0xf bank_mask:0xf
	v_mov_b32_dpp v78, v38 row_shr:1 row_mask:0xf bank_mask:0xf
	v_mov_b32_dpp v79, v39 row_shr:1 row_mask:0xf bank_mask:0xf
	v_mov_b32_dpp v80, v40 row_shr:1 row_mask:0xf bank_mask:0xf
	v_mov_b32_dpp v81, v41 row_shr:1 row_mask:0xf bank_mask:0xf
	v_cndmask_b32_e64 v35, v35, 0, vcc
	v_cndmask_b32_e64 v34, v34, 0, vcc
	v_cndmask_b32_e64 v37, v37, 0, vcc
	v_cndmask_b32_e64 v36, v36, 0, vcc
	v_cndmask_b32_e64 v81, v81, 0, vcc
	v_cndmask_b32_e64 v80, v80, 0, vcc
	v_cndmask_b32_e64 v79, v79, 0, vcc
	v_cndmask_b32_e64 v78, v78, 0, vcc
	v_pk_fma_f32 v[36:37], v[214:215], v[36:37], v[226:227]
	v_pk_fma_f32 v[34:35], v[212:213], v[34:35], v[224:225]
	v_pk_fma_f32 v[36:37], v[218:219], v[80:81], v[36:37]
	v_pk_fma_f32 v[34:35], v[216:217], v[78:79], v[34:35]
	v_pk_fma_f32 v[96:97], v[100:101], v[222:223], v[36:37]
	v_pk_fma_f32 v[94:95], v[98:99], v[220:221], v[34:35]
	v_pk_fma_f32 v[34:35], v[214:215], v[80:81], v[226:227]
	v_pk_fma_f32 v[36:37], v[212:213], v[78:79], v[224:225]
	v_pk_fma_f32 v[34:35], v[100:101], v[218:219], v[34:35]
	v_pk_fma_f32 v[36:37], v[98:99], v[216:217], v[36:37]
	v_cndmask_b32_e64 v79, v101, 0, s[4:5]
	v_cndmask_b32_e64 v78, v100, 0, s[4:5]
	v_cndmask_b32_e64 v81, v99, 0, s[4:5]
	v_cndmask_b32_e64 v80, v98, 0, s[4:5]
	v_pk_fma_f32 v[88:89], v[104:105], v[222:223], v[34:35]
	v_pk_fma_f32 v[86:87], v[102:103], v[220:221], v[36:37]
	v_cndmask_b32_e64 v35, v103, 0, s[4:5]
	v_cndmask_b32_e64 v34, v102, 0, s[4:5]
	v_cndmask_b32_e64 v37, v105, 0, s[4:5]
	v_cndmask_b32_e64 v36, v104, 0, s[4:5]
	v_pk_fma_f32 v[80:81], v[80:81], v[212:213], v[224:225]
	v_pk_fma_f32 v[78:79], v[78:79], v[214:215], v[226:227]
	s_nop 0
	v_pk_fma_f32 v[152:153], v[36:37], v[218:219], v[78:79]
	v_pk_fma_f32 v[78:79], v[34:35], v[216:217], v[80:81]
	v_pk_fma_f32 v[34:35], v[34:35], v[212:213], v[224:225]
	v_pk_fma_f32 v[36:37], v[36:37], v[214:215], v[226:227]
	v_pk_fma_f32 v[34:35], v[26:27], v[216:217], v[34:35]
	v_pk_fma_f32 v[36:37], v[28:29], v[218:219], v[36:37]
	v_pk_fma_f32 v[78:79], v[26:27], v[220:221], v[78:79]
	v_pk_fma_f32 v[80:81], v[28:29], v[222:223], v[152:153]
	v_pk_fma_f32 v[34:35], v[38:39], v[220:221], v[34:35]
	v_pk_fma_f32 v[36:37], v[40:41], v[222:223], v[36:37]
	s_cbranch_execnz .LBB0_608
